# row passes a,b: f32 residual stream loads and stores marked nt (streaming), freeing cache for reused activations
# speedup vs baseline: 1.0033x; 1.0011x over previous
.LBB0_289:
	v_lshl_add_u64 v[0:1], s[16:17], 0, v[192:193]
	v_add_co_u32_e32 v4, vcc, 0x1000, v0
	v_lshl_add_u64 v[32:33], s[20:21], 0, v[52:53]
	s_nop 0
	v_addc_co_u32_e32 v5, vcc, 0, v1, vcc
	v_add_co_u32_e32 v34, vcc, 0x1ba00000, v32
	global_load_dwordx4 v[8:11], v[0:1], off offset:16 nt
	global_load_dwordx4 v[12:15], v[0:1], off nt
	global_load_dwordx4 v[16:19], v[0:1], off offset:2064 nt
	global_load_dwordx4 v[20:23], v[0:1], off offset:2048 nt
	v_lshl_add_u64 v[2:3], v[0:1], 0, s[28:29]
	v_lshl_add_u64 v[0:1], v[0:1], 0, s[26:27]
	v_addc_co_u32_e32 v35, vcc, 0, v33, vcc
	global_load_dwordx4 v[28:31], v[4:5], off nt
	global_load_dwordx4 v[24:27], v[2:3], off offset:16 nt
	s_nop 0
	global_load_dwordx4 v[4:7], v[4:5], off offset:2048 nt
	s_nop 0
	global_load_dwordx4 v[0:3], v[0:1], off offset:16 nt
	s_nop 0
	global_load_dwordx4 v[64:67], v[34:35], off
	global_load_dwordx4 v[68:71], v[34:35], off offset:1024
	global_load_dwordx4 v[58:61], v[34:35], off offset:2048
	global_load_dwordx4 v[88:91], v[34:35], off offset:3072
	s_mov_b32 s4, 0xf800000
	s_waitcnt vmcnt(3)
	v_and_b32_e32 v75, 0xffff0000, v66
	v_and_b32_e32 v74, 0xffff0000, v64
	v_and_b32_e32 v79, 0xffff0000, v67
	v_and_b32_e32 v78, 0xffff0000, v65
	v_lshlrev_b32_e32 v73, 16, v66
	v_lshlrev_b32_e32 v72, 16, v64
	v_lshlrev_b32_e32 v77, 16, v67
	v_lshlrev_b32_e32 v76, 16, v65
	v_pk_mul_f32 v[34:35], v[74:75], v[74:75]
	v_pk_mul_f32 v[64:65], v[78:79], v[78:79]
	v_pk_fma_f32 v[34:35], v[72:73], v[72:73], v[34:35]
	v_pk_fma_f32 v[64:65], v[76:77], v[76:77], v[64:65]
	s_waitcnt vmcnt(2)
	v_lshlrev_b32_e32 v32, 16, v70
	v_pk_add_f32 v[34:35], v[34:35], v[64:65]
	v_and_b32_e32 v33, 0xffff0000, v70
	v_pk_add_f32 v[64:65], v[34:35], v[34:35] op_sel_hi:[0,1]
	v_lshlrev_b32_e32 v35, 16, v69
	v_lshlrev_b32_e32 v34, 16, v68
	v_and_b32_e32 v69, 0xffff0000, v69
	v_and_b32_e32 v68, 0xffff0000, v68
	s_waitcnt vmcnt(1)
	v_lshlrev_b32_e32 v36, 16, v58
	v_pk_mul_f32 v[66:67], v[68:69], v[68:69]
	v_lshlrev_b32_e32 v70, 16, v71
	s_waitcnt vmcnt(0)
	v_lshlrev_b32_e32 v56, 16, v90
	v_and_b32_e32 v85, 0xffff0000, v90
	v_lshlrev_b32_e32 v54, 16, v91
	v_and_b32_e32 v55, 0xffff0000, v91
	v_pk_fma_f32 v[66:67], v[34:35], v[34:35], v[66:67]
	v_mul_f32_e32 v37, v32, v32
	v_mul_f32_e32 v91, v33, v33
	v_and_b32_e32 v71, 0xffff0000, v71
	v_mul_f32_e32 v62, v70, v70
	v_mov_b32_e32 v90, v36
	v_and_b32_e32 v86, 0xffff0000, v58
	v_lshlrev_b32_e32 v38, 16, v59
	v_and_b32_e32 v39, 0xffff0000, v59
	v_pk_add_f32 v[66:67], v[66:67], v[66:67] op_sel_hi:[0,1]
	v_pk_fma_f32 v[92:93], v[70:71], v[70:71], v[62:63] op_sel_hi:[1,1,0]
	v_pk_add_f32 v[90:91], v[36:37], v[90:91]
	v_mul_f32_e32 v92, v86, v86
	v_mul_f32_e32 v64, v38, v38
	v_mul_f32_e32 v66, v39, v39
	v_mul_f32_e32 v94, v36, v36
	v_mov_b32_e32 v95, v91
	v_pk_add_f32 v[90:91], v[94:95], v[92:93]
	v_pk_add_f32 v[64:65], v[64:65], v[66:67]
	v_and_b32_e32 v67, 0xffff0000, v61
	v_pk_add_f32 v[64:65], v[90:91], v[64:65]
	v_and_b32_e32 v66, 0xffff0000, v60
	v_pk_add_f32 v[90:91], v[64:65], v[64:65] op_sel_hi:[0,1]
	v_lshlrev_b32_e32 v65, 16, v61
	v_lshlrev_b32_e32 v64, 16, v60
	v_pk_mul_f32 v[60:61], v[66:67], v[66:67]
	v_lshlrev_b32_e32 v58, 16, v88
	v_pk_fma_f32 v[60:61], v[64:65], v[64:65], v[60:61]
	v_and_b32_e32 v59, 0xffff0000, v88
	v_pk_add_f32 v[92:93], v[60:61], v[60:61] op_sel_hi:[0,1]
	v_lshlrev_b32_e32 v60, 16, v89
	v_mul_f32_e32 v57, v58, v58
	v_mul_f32_e32 v95, v59, v59
	v_and_b32_e32 v61, 0xffff0000, v89
	v_mul_f32_e32 v62, v60, v60
	v_mov_b32_e32 v94, v56
	v_pk_fma_f32 v[88:89], v[60:61], v[60:61], v[62:63] op_sel_hi:[1,1,0]
	v_pk_add_f32 v[94:95], v[56:57], v[94:95]
	v_mul_f32_e32 v88, v85, v85
	v_mul_f32_e32 v92, v54, v54
	v_mul_f32_e32 v90, v55, v55
	v_mul_f32_e32 v96, v56, v56
	v_mov_b32_e32 v97, v95
	v_pk_add_f32 v[88:89], v[96:97], v[88:89]
	v_pk_add_f32 v[90:91], v[92:93], v[90:91]
	v_mov_b32_e32 v96, v72
	v_pk_add_f32 v[88:89], v[88:89], v[90:91]
	v_mov_b32_e32 v97, v74
	v_add_f32_e32 v37, v88, v89
	ds_bpermute_b32 v57, v63, v37
	v_mov_b32_e32 v74, v73
	s_waitcnt lgkmcnt(0)
	v_add_f32_e32 v37, v37, v57
	ds_bpermute_b32 v57, v80, v37
	s_waitcnt lgkmcnt(0)
	v_add_f32_e32 v37, v37, v57
	ds_bpermute_b32 v57, v81, v37
	s_waitcnt lgkmcnt(0)
	v_add_f32_e32 v37, v37, v57
	ds_bpermute_b32 v57, v82, v37
	s_waitcnt lgkmcnt(0)
	v_add_f32_e32 v37, v37, v57
	ds_bpermute_b32 v57, v83, v37
	s_waitcnt lgkmcnt(0)
	v_add_f32_e32 v37, v37, v57
	ds_bpermute_b32 v57, v84, v37
	s_waitcnt lgkmcnt(0)
	v_add_f32_e32 v37, v37, v57
	v_fmamk_f32 v37, v37, 0x3a000000, v219
	v_cmp_gt_f32_e32 vcc, s4, v37
	v_mul_f32_e32 v57, 0x4f800000, v37
	s_nop 0
	v_cndmask_b32_e32 v37, v37, v57, vcc
	v_sqrt_f32_e32 v57, v37
	s_nop 0
	v_add_u32_e32 v62, -1, v57
	v_fma_f32 v87, -v62, v57, v37
	v_cmp_ge_f32_e64 s[6:7], 0, v87
	v_add_u32_e32 v87, 1, v57
	s_nop 0
	v_cndmask_b32_e64 v62, v57, v62, s[6:7]
	v_fma_f32 v57, -v87, v57, v37
	v_cmp_lt_f32_e64 s[6:7], 0, v57
	s_nop 1
	v_cndmask_b32_e64 v57, v62, v87, s[6:7]
	v_mul_f32_e32 v62, 0x37800000, v57
	v_cndmask_b32_e32 v57, v57, v62, vcc
	v_cmp_class_f32_e32 vcc, v37, v220
	s_nop 1
	v_cndmask_b32_e32 v37, v57, v37, vcc
	v_div_scale_f32 v57, s[4:5], v37, v37, 0.5
	v_rcp_f32_e32 v62, v57
	s_nop 0
	v_fma_f32 v87, -v57, v62, 1.0
	v_fmac_f32_e32 v62, v87, v62
	v_div_scale_f32 v87, vcc, 0.5, v37, 0.5
	v_mul_f32_e32 v88, v87, v62
	v_fma_f32 v89, -v57, v88, v87
	v_fmac_f32_e32 v88, v89, v62
	v_fma_f32 v57, -v57, v88, v87
	v_div_fmas_f32 v57, v57, v62, v88
	v_mov_b64_e32 v[88:89], v[100:101]
	v_mov_b64_e32 v[90:91], v[102:103]
	v_mov_b64_e32 v[92:93], v[104:105]
	v_mov_b64_e32 v[94:95], v[106:107]
	v_div_fixup_f32 v62, v57, v37, 0.5
	v_mov_b32_e32 v37, v86
	v_mov_b32_e32 v57, v85
	s_andn2_b64 vcc, exec, s[10:11]
	v_pk_mul_f32 v[72:73], v[88:89], v[74:75]
	v_pk_mul_f32 v[92:93], v[92:93], v[96:97]
	v_mov_b32_e32 v97, v78
	v_mov_b32_e32 v78, v77
	v_pk_mul_f32 v[74:75], v[90:91], v[78:79]
	v_mov_b32_e32 v96, v76
	v_pk_fma_f32 v[10:11], v[74:75], v[62:63], v[10:11] op_sel_hi:[1,0,1]
	v_pk_fma_f32 v[8:9], v[72:73], v[62:63], v[8:9] op_sel_hi:[1,0,1]
	v_mov_b64_e32 v[72:73], v[108:109]
	v_mov_b64_e32 v[74:75], v[110:111]
	v_mov_b64_e32 v[76:77], v[112:113]
	v_mov_b64_e32 v[78:79], v[114:115]
	v_mov_b32_e32 v89, v68
	v_mov_b32_e32 v68, v35
	v_mov_b32_e32 v88, v34
	v_pk_mul_f32 v[94:95], v[94:95], v[96:97]
	v_pk_fma_f32 v[12:13], v[92:93], v[62:63], v[12:13] op_sel_hi:[1,0,1]
	v_pk_fma_f32 v[14:15], v[94:95], v[62:63], v[14:15] op_sel_hi:[1,0,1]
	v_pk_mul_f32 v[32:33], v[72:73], v[32:33]
	v_pk_mul_f32 v[34:35], v[78:79], v[68:69]
	v_pk_fma_f32 v[16:17], v[32:33], v[62:63], v[16:17] op_sel_hi:[1,0,1]
	v_pk_fma_f32 v[22:23], v[34:35], v[62:63], v[22:23] op_sel_hi:[1,0,1]
	v_pk_mul_f32 v[34:35], v[74:75], v[70:71]
	v_pk_mul_f32 v[76:77], v[76:77], v[88:89]
	v_pk_fma_f32 v[18:19], v[34:35], v[62:63], v[18:19] op_sel_hi:[1,0,1]
	v_mov_b64_e32 v[32:33], v[116:117]
	v_mov_b64_e32 v[34:35], v[118:119]
	v_mov_b64_e32 v[68:69], v[120:121]
	v_mov_b64_e32 v[70:71], v[122:123]
	v_pk_fma_f32 v[20:21], v[76:77], v[62:63], v[20:21] op_sel_hi:[1,0,1]
	v_pk_mul_f32 v[36:37], v[68:69], v[36:37]
	s_nop 0
	v_pk_fma_f32 v[28:29], v[36:37], v[62:63], v[28:29] op_sel_hi:[1,0,1]
	v_mov_b32_e32 v36, v64
	v_mov_b32_e32 v37, v66
	v_mov_b32_e32 v66, v65
	v_pk_mul_f32 v[38:39], v[70:71], v[38:39]
	v_pk_mul_f32 v[32:33], v[32:33], v[36:37]
	v_pk_mul_f32 v[34:35], v[34:35], v[66:67]
	v_pk_fma_f32 v[30:31], v[38:39], v[62:63], v[30:31] op_sel_hi:[1,0,1]
	v_pk_fma_f32 v[26:27], v[34:35], v[62:63], v[26:27] op_sel_hi:[1,0,1]
	v_pk_fma_f32 v[24:25], v[32:33], v[62:63], v[24:25] op_sel_hi:[1,0,1]
	v_mov_b64_e32 v[32:33], v[124:125]
	v_mov_b64_e32 v[34:35], v[126:127]
	v_mov_b64_e32 v[36:37], v[128:129]
	v_mov_b64_e32 v[38:39], v[130:131]
	v_pk_mul_f32 v[32:33], v[32:33], v[56:57]
	v_pk_mul_f32 v[36:37], v[36:37], v[58:59]
	v_pk_mul_f32 v[38:39], v[38:39], v[60:61]
	v_pk_mul_f32 v[34:35], v[34:35], v[54:55]
	v_pk_fma_f32 v[6:7], v[38:39], v[62:63], v[6:7] op_sel_hi:[1,0,1]
	v_pk_fma_f32 v[4:5], v[36:37], v[62:63], v[4:5] op_sel_hi:[1,0,1]
	v_pk_fma_f32 v[2:3], v[34:35], v[62:63], v[2:3] op_sel_hi:[1,0,1]
	v_pk_fma_f32 v[0:1], v[32:33], v[62:63], v[0:1] op_sel_hi:[1,0,1]
	s_cbranch_vccnz .LBB0_291
	v_lshl_add_u64 v[32:33], s[22:23], 0, v[192:193]
	global_store_dwordx4 v[32:33], v[12:15], off nt
	global_store_dwordx4 v[32:33], v[8:11], off offset:16 nt
	global_store_dwordx4 v[32:33], v[20:23], off offset:2048 nt
	global_store_dwordx4 v[32:33], v[16:19], off offset:2064 nt
	v_add_co_u32_e32 v32, vcc, 0x1000, v32
	s_nop 1
	v_addc_co_u32_e32 v33, vcc, 0, v33, vcc
	global_store_dwordx4 v[32:33], v[28:31], off nt
	global_store_dwordx4 v[32:33], v[24:27], off offset:16 nt
	global_store_dwordx4 v[32:33], v[4:7], off offset:2048 nt
	global_store_dwordx4 v[32:33], v[0:3], off offset:2064 nt

.LBB0_746:
	v_lshl_add_u64 v[0:1], s[12:13], 0, v[192:193]
	v_add_co_u32_e32 v4, vcc, 0x1000, v0
	v_lshl_add_u64 v[32:33], s[16:17], 0, v[52:53]
	s_nop 0
	v_addc_co_u32_e32 v5, vcc, 0, v1, vcc
	v_add_co_u32_e32 v34, vcc, 0x1ba00000, v32
	global_load_dwordx4 v[8:11], v[0:1], off offset:16 nt
	global_load_dwordx4 v[12:15], v[0:1], off nt
	global_load_dwordx4 v[16:19], v[0:1], off offset:2064 nt
	global_load_dwordx4 v[20:23], v[0:1], off offset:2048 nt
	v_lshl_add_u64 v[2:3], v[0:1], 0, s[26:27]
	v_lshl_add_u64 v[0:1], v[0:1], 0, s[24:25]
	v_addc_co_u32_e32 v35, vcc, 0, v33, vcc
	global_load_dwordx4 v[28:31], v[4:5], off nt
	global_load_dwordx4 v[24:27], v[2:3], off offset:16 nt
	s_nop 0
	global_load_dwordx4 v[4:7], v[4:5], off offset:2048 nt
	s_nop 0
	global_load_dwordx4 v[0:3], v[0:1], off offset:16 nt
	s_nop 0
	global_load_dwordx4 v[64:67], v[34:35], off
	global_load_dwordx4 v[68:71], v[34:35], off offset:1024
	global_load_dwordx4 v[58:61], v[34:35], off offset:2048
	global_load_dwordx4 v[82:85], v[34:35], off offset:3072
	s_mov_b32 s4, 0xf800000
	s_waitcnt vmcnt(3)
	v_and_b32_e32 v75, 0xffff0000, v66
	v_and_b32_e32 v74, 0xffff0000, v64
	v_and_b32_e32 v79, 0xffff0000, v67
	v_and_b32_e32 v78, 0xffff0000, v65
	v_lshlrev_b32_e32 v73, 16, v66
	v_lshlrev_b32_e32 v72, 16, v64
	v_lshlrev_b32_e32 v77, 16, v67
	v_lshlrev_b32_e32 v76, 16, v65
	v_pk_mul_f32 v[34:35], v[74:75], v[74:75]
	v_pk_mul_f32 v[64:65], v[78:79], v[78:79]
	v_pk_fma_f32 v[34:35], v[72:73], v[72:73], v[34:35]
	v_pk_fma_f32 v[64:65], v[76:77], v[76:77], v[64:65]
	s_waitcnt vmcnt(2)
	v_lshlrev_b32_e32 v32, 16, v70
	v_pk_add_f32 v[34:35], v[34:35], v[64:65]
	v_and_b32_e32 v33, 0xffff0000, v70
	v_pk_add_f32 v[64:65], v[34:35], v[34:35] op_sel_hi:[0,1]
	v_lshlrev_b32_e32 v35, 16, v69
	v_lshlrev_b32_e32 v34, 16, v68
	v_and_b32_e32 v69, 0xffff0000, v69
	v_and_b32_e32 v68, 0xffff0000, v68
	s_waitcnt vmcnt(1)
	v_lshlrev_b32_e32 v36, 16, v58
	v_pk_mul_f32 v[66:67], v[68:69], v[68:69]
	v_lshlrev_b32_e32 v70, 16, v71
	s_waitcnt vmcnt(0)
	v_lshlrev_b32_e32 v56, 16, v84
	v_and_b32_e32 v63, 0xffff0000, v84
	v_lshlrev_b32_e32 v54, 16, v85
	v_and_b32_e32 v55, 0xffff0000, v85
	v_pk_fma_f32 v[66:67], v[34:35], v[34:35], v[66:67]
	v_mul_f32_e32 v37, v32, v32
	v_mul_f32_e32 v85, v33, v33
	v_and_b32_e32 v71, 0xffff0000, v71
	v_mul_f32_e32 v62, v70, v70
	v_mov_b32_e32 v84, v36
	v_and_b32_e32 v80, 0xffff0000, v58
	v_lshlrev_b32_e32 v38, 16, v59
	v_and_b32_e32 v39, 0xffff0000, v59
	v_pk_add_f32 v[66:67], v[66:67], v[66:67] op_sel_hi:[0,1]
	v_pk_fma_f32 v[86:87], v[70:71], v[70:71], v[62:63] op_sel_hi:[1,1,0]
	v_pk_add_f32 v[84:85], v[36:37], v[84:85]
	v_mul_f32_e32 v86, v80, v80
	v_mul_f32_e32 v64, v38, v38
	v_mul_f32_e32 v66, v39, v39
	v_mul_f32_e32 v88, v36, v36
	v_mov_b32_e32 v89, v85
	v_pk_add_f32 v[84:85], v[88:89], v[86:87]
	v_pk_add_f32 v[64:65], v[64:65], v[66:67]
	v_and_b32_e32 v67, 0xffff0000, v61
	v_pk_add_f32 v[64:65], v[84:85], v[64:65]
	v_and_b32_e32 v66, 0xffff0000, v60
	v_pk_add_f32 v[84:85], v[64:65], v[64:65] op_sel_hi:[0,1]
	v_lshlrev_b32_e32 v65, 16, v61
	v_lshlrev_b32_e32 v64, 16, v60
	v_pk_mul_f32 v[60:61], v[66:67], v[66:67]
	v_lshlrev_b32_e32 v58, 16, v82
	v_pk_fma_f32 v[60:61], v[64:65], v[64:65], v[60:61]
	v_and_b32_e32 v59, 0xffff0000, v82
	v_pk_add_f32 v[86:87], v[60:61], v[60:61] op_sel_hi:[0,1]
	v_lshlrev_b32_e32 v60, 16, v83
	v_mul_f32_e32 v57, v58, v58
	v_mul_f32_e32 v89, v59, v59
	v_and_b32_e32 v61, 0xffff0000, v83
	v_mul_f32_e32 v62, v60, v60
	v_mov_b32_e32 v88, v56
	v_pk_fma_f32 v[82:83], v[60:61], v[60:61], v[62:63] op_sel_hi:[1,1,0]
	v_pk_add_f32 v[88:89], v[56:57], v[88:89]
	v_mul_f32_e32 v82, v63, v63
	v_mul_f32_e32 v86, v54, v54
	v_mul_f32_e32 v84, v55, v55
	v_mul_f32_e32 v90, v56, v56
	v_mov_b32_e32 v91, v89
	v_pk_add_f32 v[82:83], v[90:91], v[82:83]
	v_pk_add_f32 v[84:85], v[86:87], v[84:85]
	v_mov_b32_e32 v90, v72
	v_pk_add_f32 v[82:83], v[82:83], v[84:85]
	v_mov_b32_e32 v91, v74
	v_add_f32_e32 v37, v82, v83
	ds_bpermute_b32 v57, v230, v37
	v_mov_b32_e32 v74, v73
	s_waitcnt lgkmcnt(0)
	v_add_f32_e32 v37, v37, v57
	ds_bpermute_b32 v57, v231, v37
	s_waitcnt lgkmcnt(0)
	v_add_f32_e32 v37, v37, v57
	ds_bpermute_b32 v57, v232, v37
	s_waitcnt lgkmcnt(0)
	v_add_f32_e32 v37, v37, v57
	ds_bpermute_b32 v57, v233, v37
	s_waitcnt lgkmcnt(0)
	v_add_f32_e32 v37, v37, v57
	ds_bpermute_b32 v57, v234, v37
	s_waitcnt lgkmcnt(0)
	v_add_f32_e32 v37, v37, v57
	ds_bpermute_b32 v57, v235, v37
	s_waitcnt lgkmcnt(0)
	v_add_f32_e32 v37, v37, v57
	v_fmamk_f32 v37, v37, 0x3a000000, v219
	v_cmp_gt_f32_e32 vcc, s4, v37
	v_mul_f32_e32 v57, 0x4f800000, v37
	s_nop 0
	v_cndmask_b32_e32 v37, v37, v57, vcc
	v_sqrt_f32_e32 v57, v37
	s_nop 0
	v_add_u32_e32 v62, -1, v57
	v_fma_f32 v81, -v62, v57, v37
	v_cmp_ge_f32_e64 s[4:5], 0, v81
	v_add_u32_e32 v81, 1, v57
	s_nop 0
	v_cndmask_b32_e64 v62, v57, v62, s[4:5]
	v_fma_f32 v57, -v81, v57, v37
	v_cmp_lt_f32_e64 s[4:5], 0, v57
	s_nop 1
	v_cndmask_b32_e64 v57, v62, v81, s[4:5]
	v_mul_f32_e32 v62, 0x37800000, v57
	v_cndmask_b32_e32 v57, v57, v62, vcc
	v_cmp_class_f32_e32 vcc, v37, v220
	s_nop 1
	v_cndmask_b32_e32 v37, v57, v37, vcc
	v_div_scale_f32 v57, s[4:5], v37, v37, 1.0
	v_rcp_f32_e32 v62, v57
	s_nop 0
	v_fma_f32 v81, -v57, v62, 1.0
	v_fmac_f32_e32 v62, v81, v62
	v_div_scale_f32 v81, vcc, 1.0, v37, 1.0
	v_mul_f32_e32 v82, v81, v62
	v_fma_f32 v83, -v57, v82, v81
	v_fmac_f32_e32 v82, v83, v62
	v_fma_f32 v57, -v57, v82, v81
	v_div_fmas_f32 v57, v57, v62, v82
	v_mov_b64_e32 v[82:83], v[100:101]
	v_mov_b64_e32 v[84:85], v[102:103]
	v_mov_b64_e32 v[86:87], v[104:105]
	v_mov_b64_e32 v[88:89], v[106:107]
	v_div_fixup_f32 v62, v57, v37, 1.0
	v_mov_b32_e32 v37, v80
	v_mov_b32_e32 v57, v63
	s_andn2_b64 vcc, exec, s[8:9]
	v_pk_mul_f32 v[72:73], v[82:83], v[74:75]
	v_pk_mul_f32 v[86:87], v[86:87], v[90:91]
	v_mov_b32_e32 v91, v78
	v_mov_b32_e32 v78, v77
	v_pk_mul_f32 v[74:75], v[84:85], v[78:79]
	v_mov_b32_e32 v90, v76
	v_pk_fma_f32 v[10:11], v[74:75], v[62:63], v[10:11] op_sel_hi:[1,0,1]
	v_pk_fma_f32 v[8:9], v[72:73], v[62:63], v[8:9] op_sel_hi:[1,0,1]
	v_mov_b64_e32 v[72:73], v[108:109]
	v_mov_b64_e32 v[74:75], v[110:111]
	v_mov_b64_e32 v[76:77], v[112:113]
	v_mov_b64_e32 v[78:79], v[114:115]
	v_mov_b32_e32 v83, v68
	v_mov_b32_e32 v68, v35
	v_mov_b32_e32 v82, v34
	v_pk_mul_f32 v[88:89], v[88:89], v[90:91]
	v_pk_fma_f32 v[12:13], v[86:87], v[62:63], v[12:13] op_sel_hi:[1,0,1]
	v_pk_fma_f32 v[14:15], v[88:89], v[62:63], v[14:15] op_sel_hi:[1,0,1]
	v_pk_mul_f32 v[32:33], v[72:73], v[32:33]
	v_pk_mul_f32 v[34:35], v[78:79], v[68:69]
	v_pk_fma_f32 v[16:17], v[32:33], v[62:63], v[16:17] op_sel_hi:[1,0,1]
	v_pk_fma_f32 v[22:23], v[34:35], v[62:63], v[22:23] op_sel_hi:[1,0,1]
	v_pk_mul_f32 v[34:35], v[74:75], v[70:71]
	v_pk_mul_f32 v[76:77], v[76:77], v[82:83]
	v_pk_fma_f32 v[18:19], v[34:35], v[62:63], v[18:19] op_sel_hi:[1,0,1]
	v_mov_b64_e32 v[32:33], v[116:117]
	v_mov_b64_e32 v[34:35], v[118:119]
	v_mov_b64_e32 v[68:69], v[120:121]
	v_mov_b64_e32 v[70:71], v[122:123]
	v_pk_fma_f32 v[20:21], v[76:77], v[62:63], v[20:21] op_sel_hi:[1,0,1]
	v_pk_mul_f32 v[36:37], v[68:69], v[36:37]
	s_nop 0
	v_pk_fma_f32 v[28:29], v[36:37], v[62:63], v[28:29] op_sel_hi:[1,0,1]
	v_mov_b32_e32 v36, v64
	v_mov_b32_e32 v37, v66
	v_mov_b32_e32 v66, v65
	v_pk_mul_f32 v[38:39], v[70:71], v[38:39]
	v_pk_mul_f32 v[32:33], v[32:33], v[36:37]
	v_pk_mul_f32 v[34:35], v[34:35], v[66:67]
	v_pk_fma_f32 v[30:31], v[38:39], v[62:63], v[30:31] op_sel_hi:[1,0,1]
	v_pk_fma_f32 v[26:27], v[34:35], v[62:63], v[26:27] op_sel_hi:[1,0,1]
	v_pk_fma_f32 v[24:25], v[32:33], v[62:63], v[24:25] op_sel_hi:[1,0,1]
	v_mov_b64_e32 v[32:33], v[124:125]
	v_mov_b64_e32 v[34:35], v[126:127]
	v_mov_b64_e32 v[36:37], v[128:129]
	v_mov_b64_e32 v[38:39], v[130:131]
	v_pk_mul_f32 v[32:33], v[32:33], v[56:57]
	v_pk_mul_f32 v[36:37], v[36:37], v[58:59]
	v_pk_mul_f32 v[38:39], v[38:39], v[60:61]
	v_pk_mul_f32 v[34:35], v[34:35], v[54:55]
	v_pk_fma_f32 v[6:7], v[38:39], v[62:63], v[6:7] op_sel_hi:[1,0,1]
	v_pk_fma_f32 v[4:5], v[36:37], v[62:63], v[4:5] op_sel_hi:[1,0,1]
	v_pk_fma_f32 v[2:3], v[34:35], v[62:63], v[2:3] op_sel_hi:[1,0,1]
	v_pk_fma_f32 v[0:1], v[32:33], v[62:63], v[0:1] op_sel_hi:[1,0,1]
	s_cbranch_vccnz .LBB0_748
	v_lshl_add_u64 v[32:33], s[18:19], 0, v[192:193]
	global_store_dwordx4 v[32:33], v[12:15], off nt
	global_store_dwordx4 v[32:33], v[8:11], off offset:16 nt
	global_store_dwordx4 v[32:33], v[20:23], off offset:2048 nt
	global_store_dwordx4 v[32:33], v[16:19], off offset:2064 nt
	v_add_co_u32_e32 v32, vcc, 0x1000, v32
	s_nop 1
	v_addc_co_u32_e32 v33, vcc, 0, v33, vcc
	global_store_dwordx4 v[32:33], v[28:31], off nt
	global_store_dwordx4 v[32:33], v[24:27], off offset:16 nt
	global_store_dwordx4 v[32:33], v[4:7], off offset:2048 nt
	global_store_dwordx4 v[32:33], v[0:3], off offset:2064 nt
